# selection ranking: candidate groups wholly beyond the current block are skipped (wave-uniform branch), count split across the head-pair waves
# speedup vs baseline: 1.0099x; 1.0005x over previous
; #define LAS __attribute__((address_space(3)))
; DI void attn_phase(const Params& p, const int layer, const int wid_s) {
;     ...
; #pragma unroll
;         for (int dt = 0; dt < 4; ++dt)
; #pragma unroll
;           for (int j = 0; j < 4; ++j) fin[(hp * 16 + dt * 4 + j) * 64] = o[dt][j] * gate_c;
;       }
;       unsigned mk = (2u << cur) - 1u;
;       if (cur >= 8) {
;       float impv[8];
;       __syncthreads();
; #pragma unroll
;       for (int nt = 0; nt < 8; ++nt) {
;         const float mine = impx[(wave * 8 + nt) * 64], other = impx[((wave ^ 4) * 8 + nt) * 64];
;         const float im = hpair == 0 ? mine + other : other + mine;
;         const int jb = nt * 4 + fql;
;         const bool forced = (jb == 0) || (jb == cur) || (jb == cur - 1);
;         impv[nt] = jb <= cur ? im + (forced ? 1e6f : 0.f) : NEGF;
;         impb[jb] = impv[nt];
;       }
;       __syncthreads();
;       int cnt[8];
; #pragma unroll
;       for (int nt = 0; nt < 8; ++nt) cnt[nt] = 0;
; #pragma unroll
;       for (int i = 0; i < 8; ++i) {
;         const f32x4 r4 = *(const LAS f32x4*)(impb + 4 * i);
.LBB0_332:
	v_cvt_f32_f16_sdwa v0, v121 dst_sel:DWORD dst_unused:UNUSED_PAD src0_sel:WORD_1
	v_mul_f32_e32 v0, 0xbfb8aa3b, v0
	v_exp_f32_e32 v0, v0
	s_nop 0
	v_add_f32_e32 v0, 1.0, v0
	v_div_scale_f32 v2, s[4:5], v0, v0, 1.0
	v_rcp_f32_e32 v3, v2
	v_div_scale_f32 v5, vcc, 1.0, v0, 1.0
	s_lshl_b32 s4, 2, s54
	v_fma_f32 v6, -v2, v3, 1.0
	v_fmac_f32_e32 v3, v6, v3
	v_mul_f32_e32 v6, v5, v3
	v_fma_f32 v7, -v2, v6, v5
	v_fmac_f32_e32 v6, v7, v3
	v_fma_f32 v2, -v2, v6, v5
	v_div_fmas_f32 v2, v2, v3, v6
	v_div_fixup_f32 v0, v2, v0, 1.0
	v_mul_f32_e32 v2, v0, v36
	v_mul_f32_e32 v3, v0, v37
	v_mul_f32_e32 v5, v0, v38
	v_mul_f32_e32 v6, v0, v39
	v_mul_f32_e32 v7, v0, v28
	ds_write2st64_b32 v188, v2, v3 offset0:168 offset1:169
	ds_write2st64_b32 v188, v5, v6 offset0:170 offset1:171
	v_mul_f32_e32 v2, v0, v29
	ds_write2st64_b32 v188, v7, v2 offset0:172 offset1:173
	v_mul_f32_e32 v2, v0, v30
	v_mul_f32_e32 v3, v0, v31
	ds_write2st64_b32 v188, v2, v3 offset0:174 offset1:175
	v_mul_f32_e32 v2, v0, v32
	v_mul_f32_e32 v3, v0, v33
	ds_write2st64_b32 v188, v2, v3 offset0:176 offset1:177
	v_mul_f32_e32 v2, v0, v34
	v_mul_f32_e32 v3, v0, v35
	ds_write2st64_b32 v188, v2, v3 offset0:178 offset1:179
	v_mul_f32_e32 v2, v0, v24
	v_mul_f32_e32 v3, v0, v25
	s_add_i32 s4, s4, -1
	ds_write2st64_b32 v188, v2, v3 offset0:180 offset1:181
	v_mul_f32_e32 v2, v0, v26
	v_mul_f32_e32 v0, v0, v27
	s_and_b64 vcc, exec, s[0:1]
	v_mov_b32_e32 v5, s4
	ds_write2st64_b32 v188, v2, v0 offset0:182 offset1:183
	s_cbranch_vccnz .LBB0_334
	s_waitcnt lgkmcnt(0)
	s_barrier
	ds_read_b32 v198, v151 offset:22656
	ds_read_b32 v199, v151 offset:22912
	ds_read_b32 v200, v151 offset:23168
	ds_read_b32 v201, v151 offset:23424
	ds_read_b32 v202, v151 offset:23680
	ds_read_b32 v203, v151 offset:23936
	ds_read_b32 v204, v151 offset:24192
	ds_read_b32 v205, v151 offset:24448
	ds_read_b32 v206, v182 offset:22656
	ds_read_b32 v207, v182 offset:22912
	ds_read_b32 v208, v182 offset:23168
	ds_read_b32 v209, v182 offset:23424
	ds_read_b32 v210, v182 offset:23680
	ds_read_b32 v211, v182 offset:23936
	ds_read_b32 v212, v182 offset:24192
	ds_read_b32 v213, v182 offset:24448
	s_add_i32 s6, s54, -1
	v_lshl_add_u32 v24, v123, 2, v147
	v_add_u32_e32 v238, 0, v123
	v_add_u32_e32 v239, 4, v123
	v_add_u32_e32 v240, 8, v123
	v_add_u32_e32 v241, 12, v123
	v_add_u32_e32 v242, 16, v123
	v_add_u32_e32 v243, 20, v123
	v_add_u32_e32 v244, 24, v123
	v_add_u32_e32 v245, 28, v123
	s_waitcnt lgkmcnt(0)
	v_cmp_eq_u32_e64 s[8:9], 0, v238
	v_cmp_eq_u32_e64 s[10:11], s54, v238
	v_cmp_eq_u32_e64 s[12:13], s6, v238
	v_add_f32_e32 v198, v198, v206
	s_or_b64 s[8:9], s[8:9], s[10:11]
	s_or_b64 s[8:9], s[8:9], s[12:13]
	v_cmp_lt_i32_e64 s[14:15], s54, v238
	s_nop 0
	v_cndmask_b32_e64 v0, 0, v159, s[8:9]
	s_nop 0
	v_add_f32_e32 v198, v0, v198
	v_cndmask_b32_e64 v39, v198, v4, s[14:15]
	ds_write_b32 v24, v39 offset:4224
	v_cmp_eq_u32_e64 s[8:9], 0, v239
	v_cmp_eq_u32_e64 s[10:11], s54, v239
	v_cmp_eq_u32_e64 s[12:13], s6, v239
	v_add_f32_e32 v199, v199, v207
	s_or_b64 s[8:9], s[8:9], s[10:11]
	s_or_b64 s[8:9], s[8:9], s[12:13]
	v_cmp_lt_i32_e64 s[14:15], s54, v239
	s_nop 0
	v_cndmask_b32_e64 v0, 0, v159, s[8:9]
	s_nop 0
	v_add_f32_e32 v199, v0, v199
	v_cndmask_b32_e64 v40, v199, v4, s[14:15]
	ds_write_b32 v24, v40 offset:4240
	v_cmp_eq_u32_e64 s[8:9], 0, v240
	v_cmp_eq_u32_e64 s[10:11], s54, v240
	v_cmp_eq_u32_e64 s[12:13], s6, v240
	v_add_f32_e32 v200, v200, v208
	s_or_b64 s[8:9], s[8:9], s[10:11]
	s_or_b64 s[8:9], s[8:9], s[12:13]
	v_cmp_lt_i32_e64 s[14:15], s54, v240
	s_nop 0
	v_cndmask_b32_e64 v0, 0, v159, s[8:9]
	s_nop 0
	v_add_f32_e32 v200, v0, v200
	v_cndmask_b32_e64 v38, v200, v4, s[14:15]
	ds_write_b32 v24, v38 offset:4256
	v_cmp_eq_u32_e64 s[8:9], 0, v241
	v_cmp_eq_u32_e64 s[10:11], s54, v241
	v_cmp_eq_u32_e64 s[12:13], s6, v241
	v_add_f32_e32 v201, v201, v209
	s_or_b64 s[8:9], s[8:9], s[10:11]
	s_or_b64 s[8:9], s[8:9], s[12:13]
	v_cmp_lt_i32_e64 s[14:15], s54, v241
	s_nop 0
	v_cndmask_b32_e64 v0, 0, v159, s[8:9]
	s_nop 0
	v_add_f32_e32 v201, v0, v201
	v_cndmask_b32_e64 v37, v201, v4, s[14:15]
	ds_write_b32 v24, v37 offset:4272
	v_cmp_eq_u32_e64 s[8:9], 0, v242
	v_cmp_eq_u32_e64 s[10:11], s54, v242
	v_cmp_eq_u32_e64 s[12:13], s6, v242
	v_add_f32_e32 v202, v202, v210
	s_or_b64 s[8:9], s[8:9], s[10:11]
	s_or_b64 s[8:9], s[8:9], s[12:13]
	v_cmp_lt_i32_e64 s[14:15], s54, v242
	s_nop 0
	v_cndmask_b32_e64 v0, 0, v159, s[8:9]
	s_nop 0
	v_add_f32_e32 v202, v0, v202
	v_cndmask_b32_e64 v36, v202, v4, s[14:15]
	ds_write_b32 v24, v36 offset:4288
	v_cmp_eq_u32_e64 s[8:9], 0, v243
	v_cmp_eq_u32_e64 s[10:11], s54, v243
	v_cmp_eq_u32_e64 s[12:13], s6, v243
	v_add_f32_e32 v203, v203, v211
	s_or_b64 s[8:9], s[8:9], s[10:11]
	s_or_b64 s[8:9], s[8:9], s[12:13]
	v_cmp_lt_i32_e64 s[14:15], s54, v243
	s_nop 0
	v_cndmask_b32_e64 v0, 0, v159, s[8:9]
	s_nop 0
	v_add_f32_e32 v203, v0, v203
	v_cndmask_b32_e64 v35, v203, v4, s[14:15]
	ds_write_b32 v24, v35 offset:4304
	v_cmp_eq_u32_e64 s[8:9], 0, v244
	v_cmp_eq_u32_e64 s[10:11], s54, v244
	v_cmp_eq_u32_e64 s[12:13], s6, v244
	v_add_f32_e32 v204, v204, v212
	s_or_b64 s[8:9], s[8:9], s[10:11]
	s_or_b64 s[8:9], s[8:9], s[12:13]
	v_cmp_lt_i32_e64 s[14:15], s54, v244
	s_nop 0
	v_cndmask_b32_e64 v0, 0, v159, s[8:9]
	s_nop 0
	v_add_f32_e32 v204, v0, v204
	v_cndmask_b32_e64 v34, v204, v4, s[14:15]
	ds_write_b32 v24, v34 offset:4320
	v_cmp_eq_u32_e64 s[8:9], 0, v245
	v_cmp_eq_u32_e64 s[10:11], s54, v245
	v_cmp_eq_u32_e64 s[12:13], s6, v245
	v_add_f32_e32 v205, v205, v213
	s_or_b64 s[8:9], s[8:9], s[10:11]
	s_or_b64 s[8:9], s[8:9], s[12:13]
	v_cmp_lt_i32_e64 s[14:15], s54, v245
	s_nop 0
	v_cndmask_b32_e64 v0, 0, v159, s[8:9]
	s_nop 0
	v_add_f32_e32 v205, v0, v205
	v_cndmask_b32_e64 v33, v205, v4, s[14:15]
	ds_write_b32 v24, v33 offset:4336
	s_waitcnt lgkmcnt(0)
	s_barrier
	ds_read_b128 v[198:201], v147 offset:4224
	ds_read_b128 v[202:205], v147 offset:4240
	ds_read_b128 v[206:209], v147 offset:4256
	ds_read_b128 v[210:213], v147 offset:4272
	ds_read_b128 v[214:217], v147 offset:4288
	ds_read_b128 v[218:221], v147 offset:4304
	ds_read_b128 v[222:225], v147 offset:4320
	ds_read_b128 v[226:229], v147 offset:4336
	v_cmp_lt_i32_e64 s[6:7], 0, v123
	v_cmp_lt_i32_e64 s[8:9], 1, v123
	v_cmp_lt_i32_e64 s[10:11], 2, v123
	v_mov_b32_e32 v230, 0
	v_mov_b32_e32 v231, 0
	v_mov_b32_e32 v232, 0
	v_mov_b32_e32 v233, 0
	v_mov_b32_e32 v234, 0
	v_mov_b32_e32 v235, 0
	v_mov_b32_e32 v236, 0
	v_mov_b32_e32 v237, 0
	s_waitcnt lgkmcnt(0)
	s_and_b64 vcc, exec, s[30:31]
	s_cbranch_vccz .Lrk_lo
	s_cmp_gt_i32 s54, 15
	s_cbranch_scc1 .Lrk_do_h4
	v_mov_b32_e32 v242, 0
	s_branch .Lrk_sk_h4
; #define LAS __attribute__((address_space(3)))
; DI void attn_phase(const Params& p, const int layer, const int wid_s) {
;     ...
;       for (int i = 0; i < 8; ++i) {
;         const f32x4 r4 = *(const LAS f32x4*)(impb + 4 * i);
;         const float rv[4] = {r4[0], r4[1], r4[2], r4[3]};
; #pragma unroll
;         for (int nt = 0; nt < 8; ++nt) {
;           const float a = impv[nt]; const int ja = nt * 4 + fql;
; #pragma unroll
;           for (int c = 0; c < 4; ++c) cnt[nt] += (int)(rv[c] > a) | ((int)(rv[c] == a) & (int)((4 * i + c) < ja));
;         }
;       }
;       mk = 0;
; #pragma unroll
;       for (int nt = 0; nt < 8; ++nt) { const int ja = nt * 4 + fql; if (cnt[nt] < 8 && ja <= cur) mk |= 1u << ja; }
.Lrk_do_h4:
	v_cmp_ge_f32_e64 s[12:13], v198, v36
	v_cmp_ge_f32_e64 s[14:15], v199, v36
	v_cmp_ge_f32_e64 s[16:17], v200, v36
	v_addc_co_u32_e64 v234, s[18:19], 0, v234, s[12:13]
	v_cmp_ge_f32_e64 s[12:13], v201, v36
	v_addc_co_u32_e64 v234, s[18:19], 0, v234, s[14:15]
	v_cmp_ge_f32_e64 s[14:15], v202, v36
	v_addc_co_u32_e64 v234, s[18:19], 0, v234, s[16:17]
	v_cmp_ge_f32_e64 s[16:17], v203, v36
	v_addc_co_u32_e64 v234, s[18:19], 0, v234, s[12:13]
	v_cmp_ge_f32_e64 s[12:13], v204, v36
	v_addc_co_u32_e64 v234, s[18:19], 0, v234, s[14:15]
	v_cmp_ge_f32_e64 s[14:15], v205, v36
	v_addc_co_u32_e64 v234, s[18:19], 0, v234, s[16:17]
	v_cmp_ge_f32_e64 s[16:17], v206, v36
	v_addc_co_u32_e64 v234, s[18:19], 0, v234, s[12:13]
	v_cmp_ge_f32_e64 s[12:13], v207, v36
	v_addc_co_u32_e64 v234, s[18:19], 0, v234, s[14:15]
	v_cmp_ge_f32_e64 s[14:15], v208, v36
	v_addc_co_u32_e64 v234, s[18:19], 0, v234, s[16:17]
	v_cmp_ge_f32_e64 s[16:17], v209, v36
	v_addc_co_u32_e64 v234, s[18:19], 0, v234, s[12:13]
	v_cmp_ge_f32_e64 s[12:13], v210, v36
	v_addc_co_u32_e64 v234, s[18:19], 0, v234, s[14:15]
	v_cmp_ge_f32_e64 s[14:15], v211, v36
	v_addc_co_u32_e64 v234, s[18:19], 0, v234, s[16:17]
	v_cmp_ge_f32_e64 s[16:17], v212, v36
	v_addc_co_u32_e64 v234, s[18:19], 0, v234, s[12:13]
	v_cmp_ge_f32_e64 s[12:13], v213, v36
	v_addc_co_u32_e64 v234, s[18:19], 0, v234, s[14:15]
	v_cmp_gt_f32_e64 s[14:15], v214, v36
	v_cmp_ge_f32_e64 s[20:21], v214, v36
	s_and_b64 s[20:21], s[20:21], s[6:7]
	s_or_b64 s[14:15], s[14:15], s[20:21]
	v_addc_co_u32_e64 v234, s[18:19], 0, v234, s[16:17]
	v_cmp_gt_f32_e64 s[16:17], v215, v36
	v_cmp_ge_f32_e64 s[20:21], v215, v36
	s_and_b64 s[20:21], s[20:21], s[8:9]
	s_or_b64 s[16:17], s[16:17], s[20:21]
	v_addc_co_u32_e64 v234, s[18:19], 0, v234, s[12:13]
	v_cmp_gt_f32_e64 s[12:13], v216, v36
	v_cmp_ge_f32_e64 s[20:21], v216, v36
	s_and_b64 s[20:21], s[20:21], s[10:11]
	s_or_b64 s[12:13], s[12:13], s[20:21]
	v_addc_co_u32_e64 v234, s[18:19], 0, v234, s[14:15]
	v_cmp_gt_f32_e64 s[14:15], v217, v36
	v_addc_co_u32_e64 v234, s[18:19], 0, v234, s[16:17]
	v_cmp_gt_f32_e64 s[16:17], v218, v36
	v_addc_co_u32_e64 v234, s[18:19], 0, v234, s[12:13]
	v_cmp_gt_f32_e64 s[12:13], v219, v36
	v_addc_co_u32_e64 v234, s[18:19], 0, v234, s[14:15]
	v_cmp_gt_f32_e64 s[14:15], v220, v36
	v_addc_co_u32_e64 v234, s[18:19], 0, v234, s[16:17]
	v_cmp_gt_f32_e64 s[16:17], v221, v36
	v_addc_co_u32_e64 v234, s[18:19], 0, v234, s[12:13]
	v_cmp_gt_f32_e64 s[12:13], v222, v36
	v_addc_co_u32_e64 v234, s[18:19], 0, v234, s[14:15]
	v_cmp_gt_f32_e64 s[14:15], v223, v36
	v_addc_co_u32_e64 v234, s[18:19], 0, v234, s[16:17]
	v_cmp_gt_f32_e64 s[16:17], v224, v36
	v_addc_co_u32_e64 v234, s[18:19], 0, v234, s[12:13]
	v_cmp_gt_f32_e64 s[12:13], v225, v36
	v_addc_co_u32_e64 v234, s[18:19], 0, v234, s[14:15]
	v_cmp_gt_f32_e64 s[14:15], v226, v36
	v_addc_co_u32_e64 v234, s[18:19], 0, v234, s[16:17]
	v_cmp_gt_f32_e64 s[16:17], v227, v36
	v_addc_co_u32_e64 v234, s[18:19], 0, v234, s[12:13]
	v_cmp_gt_f32_e64 s[12:13], v228, v36
	v_addc_co_u32_e64 v234, s[18:19], 0, v234, s[14:15]
	v_cmp_gt_f32_e64 s[14:15], v229, v36
	v_addc_co_u32_e64 v234, s[18:19], 0, v234, s[16:17]
	s_nop 1
	v_addc_co_u32_e64 v234, s[18:19], 0, v234, s[12:13]
	v_addc_co_u32_e64 v234, s[18:19], 0, v234, s[14:15]
	v_cmp_gt_u32_e64 s[12:13], 8, v234
	v_cmp_ge_i32_e64 s[14:15], s54, v242
	v_lshlrev_b32_e64 v242, v242, 1
	s_and_b64 s[12:13], s[12:13], s[14:15]
	s_nop 1
	v_cndmask_b32_e64 v242, 0, v242, s[12:13]
.Lrk_sk_h4:
	s_cmp_gt_i32 s54, 19
	s_cbranch_scc1 .Lrk_do_h5
	v_mov_b32_e32 v243, 0
	s_branch .Lrk_sk_h5
.Lrk_do_h5:
	v_cmp_ge_f32_e64 s[12:13], v198, v35
	v_cmp_ge_f32_e64 s[14:15], v199, v35
	v_cmp_ge_f32_e64 s[16:17], v200, v35
	v_addc_co_u32_e64 v235, s[18:19], 0, v235, s[12:13]
	v_cmp_ge_f32_e64 s[12:13], v201, v35
	v_addc_co_u32_e64 v235, s[18:19], 0, v235, s[14:15]
	v_cmp_ge_f32_e64 s[14:15], v202, v35
	v_addc_co_u32_e64 v235, s[18:19], 0, v235, s[16:17]
	v_cmp_ge_f32_e64 s[16:17], v203, v35
	v_addc_co_u32_e64 v235, s[18:19], 0, v235, s[12:13]
	v_cmp_ge_f32_e64 s[12:13], v204, v35
	v_addc_co_u32_e64 v235, s[18:19], 0, v235, s[14:15]
	v_cmp_ge_f32_e64 s[14:15], v205, v35
	v_addc_co_u32_e64 v235, s[18:19], 0, v235, s[16:17]
	v_cmp_ge_f32_e64 s[16:17], v206, v35
	v_addc_co_u32_e64 v235, s[18:19], 0, v235, s[12:13]
	v_cmp_ge_f32_e64 s[12:13], v207, v35
	v_addc_co_u32_e64 v235, s[18:19], 0, v235, s[14:15]
	v_cmp_ge_f32_e64 s[14:15], v208, v35
	v_addc_co_u32_e64 v235, s[18:19], 0, v235, s[16:17]
	v_cmp_ge_f32_e64 s[16:17], v209, v35
	v_addc_co_u32_e64 v235, s[18:19], 0, v235, s[12:13]
	v_cmp_ge_f32_e64 s[12:13], v210, v35
	v_addc_co_u32_e64 v235, s[18:19], 0, v235, s[14:15]
	v_cmp_ge_f32_e64 s[14:15], v211, v35
	v_addc_co_u32_e64 v235, s[18:19], 0, v235, s[16:17]
	v_cmp_ge_f32_e64 s[16:17], v212, v35
	v_addc_co_u32_e64 v235, s[18:19], 0, v235, s[12:13]
	v_cmp_ge_f32_e64 s[12:13], v213, v35
	v_addc_co_u32_e64 v235, s[18:19], 0, v235, s[14:15]
	v_cmp_ge_f32_e64 s[14:15], v214, v35
	v_addc_co_u32_e64 v235, s[18:19], 0, v235, s[16:17]
	v_cmp_ge_f32_e64 s[16:17], v215, v35
	v_addc_co_u32_e64 v235, s[18:19], 0, v235, s[12:13]
	v_cmp_ge_f32_e64 s[12:13], v216, v35
	v_addc_co_u32_e64 v235, s[18:19], 0, v235, s[14:15]
	v_cmp_ge_f32_e64 s[14:15], v217, v35
	v_addc_co_u32_e64 v235, s[18:19], 0, v235, s[16:17]
	v_cmp_gt_f32_e64 s[16:17], v218, v35
	v_cmp_ge_f32_e64 s[20:21], v218, v35
	s_and_b64 s[20:21], s[20:21], s[6:7]
	s_or_b64 s[16:17], s[16:17], s[20:21]
	v_addc_co_u32_e64 v235, s[18:19], 0, v235, s[12:13]
	v_cmp_gt_f32_e64 s[12:13], v219, v35
	v_cmp_ge_f32_e64 s[20:21], v219, v35
	s_and_b64 s[20:21], s[20:21], s[8:9]
; #define LAS __attribute__((address_space(3)))
; DI void attn_phase(const Params& p, const int layer, const int wid_s) {
;     ...
;       for (int i = 0; i < 8; ++i) {
;         const f32x4 r4 = *(const LAS f32x4*)(impb + 4 * i);
;         const float rv[4] = {r4[0], r4[1], r4[2], r4[3]};
; #pragma unroll
;         for (int nt = 0; nt < 8; ++nt) {
;           const float a = impv[nt]; const int ja = nt * 4 + fql;
; #pragma unroll
;           for (int c = 0; c < 4; ++c) cnt[nt] += (int)(rv[c] > a) | ((int)(rv[c] == a) & (int)((4 * i + c) < ja));
;         }
;       }
;       mk = 0;
; #pragma unroll
;       for (int nt = 0; nt < 8; ++nt) { const int ja = nt * 4 + fql; if (cnt[nt] < 8 && ja <= cur) mk |= 1u << ja; }
	s_or_b64 s[12:13], s[12:13], s[20:21]
	v_addc_co_u32_e64 v235, s[18:19], 0, v235, s[14:15]
	v_cmp_gt_f32_e64 s[14:15], v220, v35
	v_cmp_ge_f32_e64 s[20:21], v220, v35
	s_and_b64 s[20:21], s[20:21], s[10:11]
	s_or_b64 s[14:15], s[14:15], s[20:21]
	v_addc_co_u32_e64 v235, s[18:19], 0, v235, s[16:17]
	v_cmp_gt_f32_e64 s[16:17], v221, v35
	v_addc_co_u32_e64 v235, s[18:19], 0, v235, s[12:13]
	v_cmp_gt_f32_e64 s[12:13], v222, v35
	v_addc_co_u32_e64 v235, s[18:19], 0, v235, s[14:15]
	v_cmp_gt_f32_e64 s[14:15], v223, v35
	v_addc_co_u32_e64 v235, s[18:19], 0, v235, s[16:17]
	v_cmp_gt_f32_e64 s[16:17], v224, v35
	v_addc_co_u32_e64 v235, s[18:19], 0, v235, s[12:13]
	v_cmp_gt_f32_e64 s[12:13], v225, v35
	v_addc_co_u32_e64 v235, s[18:19], 0, v235, s[14:15]
	v_cmp_gt_f32_e64 s[14:15], v226, v35
	v_addc_co_u32_e64 v235, s[18:19], 0, v235, s[16:17]
	v_cmp_gt_f32_e64 s[16:17], v227, v35
	v_addc_co_u32_e64 v235, s[18:19], 0, v235, s[12:13]
	v_cmp_gt_f32_e64 s[12:13], v228, v35
	v_addc_co_u32_e64 v235, s[18:19], 0, v235, s[14:15]
	v_cmp_gt_f32_e64 s[14:15], v229, v35
	v_addc_co_u32_e64 v235, s[18:19], 0, v235, s[16:17]
	s_nop 1
	v_addc_co_u32_e64 v235, s[18:19], 0, v235, s[12:13]
	v_addc_co_u32_e64 v235, s[18:19], 0, v235, s[14:15]
	v_cmp_gt_u32_e64 s[16:17], 8, v235
	v_cmp_ge_i32_e64 s[20:21], s54, v243
	v_lshlrev_b32_e64 v243, v243, 1
	s_and_b64 s[16:17], s[16:17], s[20:21]
	s_nop 1
	v_cndmask_b32_e64 v243, 0, v243, s[16:17]
.Lrk_sk_h5:
	s_cmp_gt_i32 s54, 23
	s_cbranch_scc1 .Lrk_do_h6
	v_mov_b32_e32 v244, 0
	s_branch .Lrk_sk_h6
.Lrk_do_h6:
	v_cmp_ge_f32_e64 s[12:13], v198, v34
	v_cmp_ge_f32_e64 s[14:15], v199, v34
	v_cmp_ge_f32_e64 s[16:17], v200, v34
	v_addc_co_u32_e64 v236, s[18:19], 0, v236, s[12:13]
	v_cmp_ge_f32_e64 s[12:13], v201, v34
	v_addc_co_u32_e64 v236, s[18:19], 0, v236, s[14:15]
	v_cmp_ge_f32_e64 s[14:15], v202, v34
	v_addc_co_u32_e64 v236, s[18:19], 0, v236, s[16:17]
	v_cmp_ge_f32_e64 s[16:17], v203, v34
	v_addc_co_u32_e64 v236, s[18:19], 0, v236, s[12:13]
	v_cmp_ge_f32_e64 s[12:13], v204, v34
	v_addc_co_u32_e64 v236, s[18:19], 0, v236, s[14:15]
	v_cmp_ge_f32_e64 s[14:15], v205, v34
	v_addc_co_u32_e64 v236, s[18:19], 0, v236, s[16:17]
	v_cmp_ge_f32_e64 s[16:17], v206, v34
	v_addc_co_u32_e64 v236, s[18:19], 0, v236, s[12:13]
	v_cmp_ge_f32_e64 s[12:13], v207, v34
	v_addc_co_u32_e64 v236, s[18:19], 0, v236, s[14:15]
	v_cmp_ge_f32_e64 s[14:15], v208, v34
	v_addc_co_u32_e64 v236, s[18:19], 0, v236, s[16:17]
	v_cmp_ge_f32_e64 s[16:17], v209, v34
	v_addc_co_u32_e64 v236, s[18:19], 0, v236, s[12:13]
	v_cmp_ge_f32_e64 s[12:13], v210, v34
	v_addc_co_u32_e64 v236, s[18:19], 0, v236, s[14:15]
	v_cmp_ge_f32_e64 s[14:15], v211, v34
	v_addc_co_u32_e64 v236, s[18:19], 0, v236, s[16:17]
	v_cmp_ge_f32_e64 s[16:17], v212, v34
	v_addc_co_u32_e64 v236, s[18:19], 0, v236, s[12:13]
	v_cmp_ge_f32_e64 s[12:13], v213, v34
	v_addc_co_u32_e64 v236, s[18:19], 0, v236, s[14:15]
	v_cmp_ge_f32_e64 s[14:15], v214, v34
	v_addc_co_u32_e64 v236, s[18:19], 0, v236, s[16:17]
	v_cmp_ge_f32_e64 s[16:17], v215, v34
	v_addc_co_u32_e64 v236, s[18:19], 0, v236, s[12:13]
	v_cmp_ge_f32_e64 s[12:13], v216, v34
	v_addc_co_u32_e64 v236, s[18:19], 0, v236, s[14:15]
	v_cmp_ge_f32_e64 s[14:15], v217, v34
	v_addc_co_u32_e64 v236, s[18:19], 0, v236, s[16:17]
	v_cmp_ge_f32_e64 s[16:17], v218, v34
	v_addc_co_u32_e64 v236, s[18:19], 0, v236, s[12:13]
	v_cmp_ge_f32_e64 s[12:13], v219, v34
	v_addc_co_u32_e64 v236, s[18:19], 0, v236, s[14:15]
	v_cmp_ge_f32_e64 s[14:15], v220, v34
	v_addc_co_u32_e64 v236, s[18:19], 0, v236, s[16:17]
	v_cmp_ge_f32_e64 s[16:17], v221, v34
	v_addc_co_u32_e64 v236, s[18:19], 0, v236, s[12:13]
	v_cmp_gt_f32_e64 s[12:13], v222, v34
	v_cmp_ge_f32_e64 s[20:21], v222, v34
	s_and_b64 s[20:21], s[20:21], s[6:7]
	s_or_b64 s[12:13], s[12:13], s[20:21]
	v_addc_co_u32_e64 v236, s[18:19], 0, v236, s[14:15]
	v_cmp_gt_f32_e64 s[14:15], v223, v34
	v_cmp_ge_f32_e64 s[20:21], v223, v34
	s_and_b64 s[20:21], s[20:21], s[8:9]
	s_or_b64 s[14:15], s[14:15], s[20:21]
	v_addc_co_u32_e64 v236, s[18:19], 0, v236, s[16:17]
	v_cmp_gt_f32_e64 s[16:17], v224, v34
	v_cmp_ge_f32_e64 s[20:21], v224, v34
	s_and_b64 s[20:21], s[20:21], s[10:11]
	s_or_b64 s[16:17], s[16:17], s[20:21]
	v_addc_co_u32_e64 v236, s[18:19], 0, v236, s[12:13]
	v_cmp_gt_f32_e64 s[12:13], v225, v34
	v_addc_co_u32_e64 v236, s[18:19], 0, v236, s[14:15]
	v_cmp_gt_f32_e64 s[14:15], v226, v34
	v_addc_co_u32_e64 v236, s[18:19], 0, v236, s[16:17]
	v_cmp_gt_f32_e64 s[16:17], v227, v34
	v_addc_co_u32_e64 v236, s[18:19], 0, v236, s[12:13]
	v_cmp_gt_f32_e64 s[12:13], v228, v34
	v_addc_co_u32_e64 v236, s[18:19], 0, v236, s[14:15]
	v_cmp_gt_f32_e64 s[14:15], v229, v34
	v_addc_co_u32_e64 v236, s[18:19], 0, v236, s[16:17]
	s_nop 1
	v_addc_co_u32_e64 v236, s[18:19], 0, v236, s[12:13]
	v_addc_co_u32_e64 v236, s[18:19], 0, v236, s[14:15]
	v_cmp_gt_u32_e64 s[12:13], 8, v236
	v_cmp_ge_i32_e64 s[14:15], s54, v244
	v_lshlrev_b32_e64 v244, v244, 1
	s_and_b64 s[12:13], s[12:13], s[14:15]
	s_nop 1
	v_cndmask_b32_e64 v244, 0, v244, s[12:13]
.Lrk_sk_h6:
	s_cmp_gt_i32 s54, 27
	s_cbranch_scc1 .Lrk_do_h7
	v_mov_b32_e32 v245, 0
	s_branch .Lrk_sk_h7
; #define LAS __attribute__((address_space(3)))
; DI void attn_phase(const Params& p, const int layer, const int wid_s) {
;     ...
;       for (int i = 0; i < 8; ++i) {
;         const f32x4 r4 = *(const LAS f32x4*)(impb + 4 * i);
;         const float rv[4] = {r4[0], r4[1], r4[2], r4[3]};
; #pragma unroll
;         for (int nt = 0; nt < 8; ++nt) {
;           const float a = impv[nt]; const int ja = nt * 4 + fql;
; #pragma unroll
;           for (int c = 0; c < 4; ++c) cnt[nt] += (int)(rv[c] > a) | ((int)(rv[c] == a) & (int)((4 * i + c) < ja));
;         }
;       }
;       mk = 0;
; #pragma unroll
;       for (int nt = 0; nt < 8; ++nt) { const int ja = nt * 4 + fql; if (cnt[nt] < 8 && ja <= cur) mk |= 1u << ja; }
.Lrk_do_h7:
	v_cmp_ge_f32_e64 s[12:13], v198, v33
	v_cmp_ge_f32_e64 s[14:15], v199, v33
	v_cmp_ge_f32_e64 s[16:17], v200, v33
	v_addc_co_u32_e64 v237, s[18:19], 0, v237, s[12:13]
	v_cmp_ge_f32_e64 s[12:13], v201, v33
	v_addc_co_u32_e64 v237, s[18:19], 0, v237, s[14:15]
	v_cmp_ge_f32_e64 s[14:15], v202, v33
	v_addc_co_u32_e64 v237, s[18:19], 0, v237, s[16:17]
	v_cmp_ge_f32_e64 s[16:17], v203, v33
	v_addc_co_u32_e64 v237, s[18:19], 0, v237, s[12:13]
	v_cmp_ge_f32_e64 s[12:13], v204, v33
	v_addc_co_u32_e64 v237, s[18:19], 0, v237, s[14:15]
	v_cmp_ge_f32_e64 s[14:15], v205, v33
	v_addc_co_u32_e64 v237, s[18:19], 0, v237, s[16:17]
	v_cmp_ge_f32_e64 s[16:17], v206, v33
	v_addc_co_u32_e64 v237, s[18:19], 0, v237, s[12:13]
	v_cmp_ge_f32_e64 s[12:13], v207, v33
	v_addc_co_u32_e64 v237, s[18:19], 0, v237, s[14:15]
	v_cmp_ge_f32_e64 s[14:15], v208, v33
	v_addc_co_u32_e64 v237, s[18:19], 0, v237, s[16:17]
	v_cmp_ge_f32_e64 s[16:17], v209, v33
	v_addc_co_u32_e64 v237, s[18:19], 0, v237, s[12:13]
	v_cmp_ge_f32_e64 s[12:13], v210, v33
	v_addc_co_u32_e64 v237, s[18:19], 0, v237, s[14:15]
	v_cmp_ge_f32_e64 s[14:15], v211, v33
	v_addc_co_u32_e64 v237, s[18:19], 0, v237, s[16:17]
	v_cmp_ge_f32_e64 s[16:17], v212, v33
	v_addc_co_u32_e64 v237, s[18:19], 0, v237, s[12:13]
	v_cmp_ge_f32_e64 s[12:13], v213, v33
	v_addc_co_u32_e64 v237, s[18:19], 0, v237, s[14:15]
	v_cmp_ge_f32_e64 s[14:15], v214, v33
	v_addc_co_u32_e64 v237, s[18:19], 0, v237, s[16:17]
	v_cmp_ge_f32_e64 s[16:17], v215, v33
	v_addc_co_u32_e64 v237, s[18:19], 0, v237, s[12:13]
	v_cmp_ge_f32_e64 s[12:13], v216, v33
	v_addc_co_u32_e64 v237, s[18:19], 0, v237, s[14:15]
	v_cmp_ge_f32_e64 s[14:15], v217, v33
	v_addc_co_u32_e64 v237, s[18:19], 0, v237, s[16:17]
	v_cmp_ge_f32_e64 s[16:17], v218, v33
	v_addc_co_u32_e64 v237, s[18:19], 0, v237, s[12:13]
	v_cmp_ge_f32_e64 s[12:13], v219, v33
	v_addc_co_u32_e64 v237, s[18:19], 0, v237, s[14:15]
	v_cmp_ge_f32_e64 s[14:15], v220, v33
	v_addc_co_u32_e64 v237, s[18:19], 0, v237, s[16:17]
	v_cmp_ge_f32_e64 s[16:17], v221, v33
	v_addc_co_u32_e64 v237, s[18:19], 0, v237, s[12:13]
	v_cmp_ge_f32_e64 s[12:13], v222, v33
	v_addc_co_u32_e64 v237, s[18:19], 0, v237, s[14:15]
	v_cmp_ge_f32_e64 s[14:15], v223, v33
	v_addc_co_u32_e64 v237, s[18:19], 0, v237, s[16:17]
	v_cmp_ge_f32_e64 s[16:17], v224, v33
	v_addc_co_u32_e64 v237, s[18:19], 0, v237, s[12:13]
	v_cmp_ge_f32_e64 s[12:13], v225, v33
	v_addc_co_u32_e64 v237, s[18:19], 0, v237, s[14:15]
	v_cmp_gt_f32_e64 s[14:15], v226, v33
	v_cmp_ge_f32_e64 s[20:21], v226, v33
	s_and_b64 s[20:21], s[20:21], s[6:7]
	s_or_b64 s[14:15], s[14:15], s[20:21]
	v_addc_co_u32_e64 v237, s[18:19], 0, v237, s[16:17]
	v_cmp_gt_f32_e64 s[16:17], v227, v33
	v_cmp_ge_f32_e64 s[20:21], v227, v33
	s_and_b64 s[20:21], s[20:21], s[8:9]
	s_or_b64 s[16:17], s[16:17], s[20:21]
	v_addc_co_u32_e64 v237, s[18:19], 0, v237, s[12:13]
	v_cmp_gt_f32_e64 s[12:13], v228, v33
	v_cmp_ge_f32_e64 s[20:21], v228, v33
	s_and_b64 s[20:21], s[20:21], s[10:11]
	s_or_b64 s[12:13], s[12:13], s[20:21]
	v_addc_co_u32_e64 v237, s[18:19], 0, v237, s[14:15]
	v_cmp_gt_f32_e64 s[14:15], v229, v33
	v_addc_co_u32_e64 v237, s[18:19], 0, v237, s[16:17]
	s_nop 1
	v_addc_co_u32_e64 v237, s[18:19], 0, v237, s[12:13]
	v_addc_co_u32_e64 v237, s[18:19], 0, v237, s[14:15]
	v_cmp_gt_u32_e64 s[16:17], 8, v237
	v_cmp_ge_i32_e64 s[20:21], s54, v245
	v_lshlrev_b32_e64 v245, v245, 1
	s_and_b64 s[16:17], s[16:17], s[20:21]
	s_nop 1
	v_cndmask_b32_e64 v245, 0, v245, s[16:17]
.Lrk_sk_h7:
	v_or_b32_e32 v0, v242, v243
	v_or3_b32 v0, v0, v244, v245
	s_branch .Lrk_join
.Lrk_lo:
	s_cmp_gt_i32 s54, -1
	s_cbranch_scc1 .Lrk_do_l0
	v_mov_b32_e32 v238, 0
	s_branch .Lrk_sk_l0
.Lrk_do_l0:
	v_cmp_gt_f32_e64 s[12:13], v198, v39
	v_cmp_ge_f32_e64 s[20:21], v198, v39
	s_and_b64 s[20:21], s[20:21], s[6:7]
	s_or_b64 s[12:13], s[12:13], s[20:21]
	v_cmp_gt_f32_e64 s[14:15], v199, v39
	v_cmp_ge_f32_e64 s[20:21], v199, v39
	s_and_b64 s[20:21], s[20:21], s[8:9]
	s_or_b64 s[14:15], s[14:15], s[20:21]
	v_cmp_gt_f32_e64 s[16:17], v200, v39
	v_cmp_ge_f32_e64 s[20:21], v200, v39
	s_and_b64 s[20:21], s[20:21], s[10:11]
	s_or_b64 s[16:17], s[16:17], s[20:21]
	v_addc_co_u32_e64 v230, s[18:19], 0, v230, s[12:13]
	v_cmp_gt_f32_e64 s[12:13], v201, v39
	v_addc_co_u32_e64 v230, s[18:19], 0, v230, s[14:15]
	v_cmp_gt_f32_e64 s[14:15], v202, v39
	v_addc_co_u32_e64 v230, s[18:19], 0, v230, s[16:17]
	v_cmp_gt_f32_e64 s[16:17], v203, v39
	v_addc_co_u32_e64 v230, s[18:19], 0, v230, s[12:13]
	v_cmp_gt_f32_e64 s[12:13], v204, v39
	v_addc_co_u32_e64 v230, s[18:19], 0, v230, s[14:15]
	v_cmp_gt_f32_e64 s[14:15], v205, v39
	v_addc_co_u32_e64 v230, s[18:19], 0, v230, s[16:17]
	v_cmp_gt_f32_e64 s[16:17], v206, v39
	v_addc_co_u32_e64 v230, s[18:19], 0, v230, s[12:13]
	v_cmp_gt_f32_e64 s[12:13], v207, v39
	v_addc_co_u32_e64 v230, s[18:19], 0, v230, s[14:15]
	v_cmp_gt_f32_e64 s[14:15], v208, v39
	v_addc_co_u32_e64 v230, s[18:19], 0, v230, s[16:17]
	v_cmp_gt_f32_e64 s[16:17], v209, v39
	v_addc_co_u32_e64 v230, s[18:19], 0, v230, s[12:13]
	v_cmp_gt_f32_e64 s[12:13], v210, v39
	v_addc_co_u32_e64 v230, s[18:19], 0, v230, s[14:15]
	v_cmp_gt_f32_e64 s[14:15], v211, v39
	v_addc_co_u32_e64 v230, s[18:19], 0, v230, s[16:17]
	v_cmp_gt_f32_e64 s[16:17], v212, v39
	v_addc_co_u32_e64 v230, s[18:19], 0, v230, s[12:13]
	v_cmp_gt_f32_e64 s[12:13], v213, v39
	v_addc_co_u32_e64 v230, s[18:19], 0, v230, s[14:15]
	v_cmp_gt_f32_e64 s[14:15], v214, v39
	v_addc_co_u32_e64 v230, s[18:19], 0, v230, s[16:17]
	v_cmp_gt_f32_e64 s[16:17], v215, v39
	v_addc_co_u32_e64 v230, s[18:19], 0, v230, s[12:13]
	v_cmp_gt_f32_e64 s[12:13], v216, v39
	v_addc_co_u32_e64 v230, s[18:19], 0, v230, s[14:15]
; #define LAS __attribute__((address_space(3)))
; DI void attn_phase(const Params& p, const int layer, const int wid_s) {
;     ...
;       for (int i = 0; i < 8; ++i) {
;         const f32x4 r4 = *(const LAS f32x4*)(impb + 4 * i);
;         const float rv[4] = {r4[0], r4[1], r4[2], r4[3]};
; #pragma unroll
;         for (int nt = 0; nt < 8; ++nt) {
;           const float a = impv[nt]; const int ja = nt * 4 + fql;
; #pragma unroll
;           for (int c = 0; c < 4; ++c) cnt[nt] += (int)(rv[c] > a) | ((int)(rv[c] == a) & (int)((4 * i + c) < ja));
;         }
;       }
;       mk = 0;
; #pragma unroll
;       for (int nt = 0; nt < 8; ++nt) { const int ja = nt * 4 + fql; if (cnt[nt] < 8 && ja <= cur) mk |= 1u << ja; }
	v_cmp_gt_f32_e64 s[14:15], v217, v39
	v_addc_co_u32_e64 v230, s[18:19], 0, v230, s[16:17]
	v_cmp_gt_f32_e64 s[16:17], v218, v39
	v_addc_co_u32_e64 v230, s[18:19], 0, v230, s[12:13]
	v_cmp_gt_f32_e64 s[12:13], v219, v39
	v_addc_co_u32_e64 v230, s[18:19], 0, v230, s[14:15]
	v_cmp_gt_f32_e64 s[14:15], v220, v39
	v_addc_co_u32_e64 v230, s[18:19], 0, v230, s[16:17]
	v_cmp_gt_f32_e64 s[16:17], v221, v39
	v_addc_co_u32_e64 v230, s[18:19], 0, v230, s[12:13]
	v_cmp_gt_f32_e64 s[12:13], v222, v39
	v_addc_co_u32_e64 v230, s[18:19], 0, v230, s[14:15]
	v_cmp_gt_f32_e64 s[14:15], v223, v39
	v_addc_co_u32_e64 v230, s[18:19], 0, v230, s[16:17]
	v_cmp_gt_f32_e64 s[16:17], v224, v39
	v_addc_co_u32_e64 v230, s[18:19], 0, v230, s[12:13]
	v_cmp_gt_f32_e64 s[12:13], v225, v39
	v_addc_co_u32_e64 v230, s[18:19], 0, v230, s[14:15]
	v_cmp_gt_f32_e64 s[14:15], v226, v39
	v_addc_co_u32_e64 v230, s[18:19], 0, v230, s[16:17]
	v_cmp_gt_f32_e64 s[16:17], v227, v39
	v_addc_co_u32_e64 v230, s[18:19], 0, v230, s[12:13]
	v_cmp_gt_f32_e64 s[12:13], v228, v39
	v_addc_co_u32_e64 v230, s[18:19], 0, v230, s[14:15]
	v_cmp_gt_f32_e64 s[14:15], v229, v39
	v_addc_co_u32_e64 v230, s[18:19], 0, v230, s[16:17]
	s_nop 1
	v_addc_co_u32_e64 v230, s[18:19], 0, v230, s[12:13]
	v_addc_co_u32_e64 v230, s[18:19], 0, v230, s[14:15]
	v_cmp_gt_u32_e64 s[12:13], 8, v230
	v_cmp_ge_i32_e64 s[14:15], s54, v238
	v_lshlrev_b32_e64 v238, v238, 1
	s_and_b64 s[12:13], s[12:13], s[14:15]
	s_nop 1
	v_cndmask_b32_e64 v238, 0, v238, s[12:13]
.Lrk_sk_l0:
	s_cmp_gt_i32 s54, 3
	s_cbranch_scc1 .Lrk_do_l1
	v_mov_b32_e32 v239, 0
	s_branch .Lrk_sk_l1
.Lrk_do_l1:
	v_cmp_ge_f32_e64 s[12:13], v198, v40
	v_cmp_ge_f32_e64 s[14:15], v199, v40
	v_cmp_ge_f32_e64 s[16:17], v200, v40
	v_addc_co_u32_e64 v231, s[18:19], 0, v231, s[12:13]
	v_cmp_ge_f32_e64 s[12:13], v201, v40
	v_addc_co_u32_e64 v231, s[18:19], 0, v231, s[14:15]
	v_cmp_gt_f32_e64 s[14:15], v202, v40
	v_cmp_ge_f32_e64 s[20:21], v202, v40
	s_and_b64 s[20:21], s[20:21], s[6:7]
	s_or_b64 s[14:15], s[14:15], s[20:21]
	v_addc_co_u32_e64 v231, s[18:19], 0, v231, s[16:17]
	v_cmp_gt_f32_e64 s[16:17], v203, v40
	v_cmp_ge_f32_e64 s[20:21], v203, v40
	s_and_b64 s[20:21], s[20:21], s[8:9]
	s_or_b64 s[16:17], s[16:17], s[20:21]
	v_addc_co_u32_e64 v231, s[18:19], 0, v231, s[12:13]
	v_cmp_gt_f32_e64 s[12:13], v204, v40
	v_cmp_ge_f32_e64 s[20:21], v204, v40
	s_and_b64 s[20:21], s[20:21], s[10:11]
	s_or_b64 s[12:13], s[12:13], s[20:21]
	v_addc_co_u32_e64 v231, s[18:19], 0, v231, s[14:15]
	v_cmp_gt_f32_e64 s[14:15], v205, v40
	v_addc_co_u32_e64 v231, s[18:19], 0, v231, s[16:17]
	v_cmp_gt_f32_e64 s[16:17], v206, v40
	v_addc_co_u32_e64 v231, s[18:19], 0, v231, s[12:13]
	v_cmp_gt_f32_e64 s[12:13], v207, v40
	v_addc_co_u32_e64 v231, s[18:19], 0, v231, s[14:15]
	v_cmp_gt_f32_e64 s[14:15], v208, v40
	v_addc_co_u32_e64 v231, s[18:19], 0, v231, s[16:17]
	v_cmp_gt_f32_e64 s[16:17], v209, v40
	v_addc_co_u32_e64 v231, s[18:19], 0, v231, s[12:13]
	v_cmp_gt_f32_e64 s[12:13], v210, v40
	v_addc_co_u32_e64 v231, s[18:19], 0, v231, s[14:15]
	v_cmp_gt_f32_e64 s[14:15], v211, v40
	v_addc_co_u32_e64 v231, s[18:19], 0, v231, s[16:17]
	v_cmp_gt_f32_e64 s[16:17], v212, v40
	v_addc_co_u32_e64 v231, s[18:19], 0, v231, s[12:13]
	v_cmp_gt_f32_e64 s[12:13], v213, v40
	v_addc_co_u32_e64 v231, s[18:19], 0, v231, s[14:15]
	v_cmp_gt_f32_e64 s[14:15], v214, v40
	v_addc_co_u32_e64 v231, s[18:19], 0, v231, s[16:17]
	v_cmp_gt_f32_e64 s[16:17], v215, v40
	v_addc_co_u32_e64 v231, s[18:19], 0, v231, s[12:13]
	v_cmp_gt_f32_e64 s[12:13], v216, v40
	v_addc_co_u32_e64 v231, s[18:19], 0, v231, s[14:15]
	v_cmp_gt_f32_e64 s[14:15], v217, v40
	v_addc_co_u32_e64 v231, s[18:19], 0, v231, s[16:17]
	v_cmp_gt_f32_e64 s[16:17], v218, v40
	v_addc_co_u32_e64 v231, s[18:19], 0, v231, s[12:13]
	v_cmp_gt_f32_e64 s[12:13], v219, v40
	v_addc_co_u32_e64 v231, s[18:19], 0, v231, s[14:15]
	v_cmp_gt_f32_e64 s[14:15], v220, v40
	v_addc_co_u32_e64 v231, s[18:19], 0, v231, s[16:17]
	v_cmp_gt_f32_e64 s[16:17], v221, v40
	v_addc_co_u32_e64 v231, s[18:19], 0, v231, s[12:13]
	v_cmp_gt_f32_e64 s[12:13], v222, v40
	v_addc_co_u32_e64 v231, s[18:19], 0, v231, s[14:15]
	v_cmp_gt_f32_e64 s[14:15], v223, v40
	v_addc_co_u32_e64 v231, s[18:19], 0, v231, s[16:17]
	v_cmp_gt_f32_e64 s[16:17], v224, v40
	v_addc_co_u32_e64 v231, s[18:19], 0, v231, s[12:13]
	v_cmp_gt_f32_e64 s[12:13], v225, v40
	v_addc_co_u32_e64 v231, s[18:19], 0, v231, s[14:15]
	v_cmp_gt_f32_e64 s[14:15], v226, v40
	v_addc_co_u32_e64 v231, s[18:19], 0, v231, s[16:17]
	v_cmp_gt_f32_e64 s[16:17], v227, v40
	v_addc_co_u32_e64 v231, s[18:19], 0, v231, s[12:13]
	v_cmp_gt_f32_e64 s[12:13], v228, v40
	v_addc_co_u32_e64 v231, s[18:19], 0, v231, s[14:15]
	v_cmp_gt_f32_e64 s[14:15], v229, v40
	v_addc_co_u32_e64 v231, s[18:19], 0, v231, s[16:17]
	s_nop 1
	v_addc_co_u32_e64 v231, s[18:19], 0, v231, s[12:13]
	v_addc_co_u32_e64 v231, s[18:19], 0, v231, s[14:15]
	v_cmp_gt_u32_e64 s[16:17], 8, v231
	v_cmp_ge_i32_e64 s[20:21], s54, v239
	v_lshlrev_b32_e64 v239, v239, 1
	s_and_b64 s[16:17], s[16:17], s[20:21]
	s_nop 1
	v_cndmask_b32_e64 v239, 0, v239, s[16:17]
.Lrk_sk_l1:
	s_cmp_gt_i32 s54, 7
	s_cbranch_scc1 .Lrk_do_l2
	v_mov_b32_e32 v240, 0
	s_branch .Lrk_sk_l2
; #define LAS __attribute__((address_space(3)))
; DI void attn_phase(const Params& p, const int layer, const int wid_s) {
;     ...
;       for (int i = 0; i < 8; ++i) {
;         const f32x4 r4 = *(const LAS f32x4*)(impb + 4 * i);
;         const float rv[4] = {r4[0], r4[1], r4[2], r4[3]};
; #pragma unroll
;         for (int nt = 0; nt < 8; ++nt) {
;           const float a = impv[nt]; const int ja = nt * 4 + fql;
; #pragma unroll
;           for (int c = 0; c < 4; ++c) cnt[nt] += (int)(rv[c] > a) | ((int)(rv[c] == a) & (int)((4 * i + c) < ja));
;         }
;       }
;       mk = 0;
; #pragma unroll
;       for (int nt = 0; nt < 8; ++nt) { const int ja = nt * 4 + fql; if (cnt[nt] < 8 && ja <= cur) mk |= 1u << ja; }
.Lrk_do_l2:
	v_cmp_ge_f32_e64 s[12:13], v198, v38
	v_cmp_ge_f32_e64 s[14:15], v199, v38
	v_cmp_ge_f32_e64 s[16:17], v200, v38
	v_addc_co_u32_e64 v232, s[18:19], 0, v232, s[12:13]
	v_cmp_ge_f32_e64 s[12:13], v201, v38
	v_addc_co_u32_e64 v232, s[18:19], 0, v232, s[14:15]
	v_cmp_ge_f32_e64 s[14:15], v202, v38
	v_addc_co_u32_e64 v232, s[18:19], 0, v232, s[16:17]
	v_cmp_ge_f32_e64 s[16:17], v203, v38
	v_addc_co_u32_e64 v232, s[18:19], 0, v232, s[12:13]
	v_cmp_ge_f32_e64 s[12:13], v204, v38
	v_addc_co_u32_e64 v232, s[18:19], 0, v232, s[14:15]
	v_cmp_ge_f32_e64 s[14:15], v205, v38
	v_addc_co_u32_e64 v232, s[18:19], 0, v232, s[16:17]
	v_cmp_gt_f32_e64 s[16:17], v206, v38
	v_cmp_ge_f32_e64 s[20:21], v206, v38
	s_and_b64 s[20:21], s[20:21], s[6:7]
	s_or_b64 s[16:17], s[16:17], s[20:21]
	v_addc_co_u32_e64 v232, s[18:19], 0, v232, s[12:13]
	v_cmp_gt_f32_e64 s[12:13], v207, v38
	v_cmp_ge_f32_e64 s[20:21], v207, v38
	s_and_b64 s[20:21], s[20:21], s[8:9]
	s_or_b64 s[12:13], s[12:13], s[20:21]
	v_addc_co_u32_e64 v232, s[18:19], 0, v232, s[14:15]
	v_cmp_gt_f32_e64 s[14:15], v208, v38
	v_cmp_ge_f32_e64 s[20:21], v208, v38
	s_and_b64 s[20:21], s[20:21], s[10:11]
	s_or_b64 s[14:15], s[14:15], s[20:21]
	v_addc_co_u32_e64 v232, s[18:19], 0, v232, s[16:17]
	v_cmp_gt_f32_e64 s[16:17], v209, v38
	v_addc_co_u32_e64 v232, s[18:19], 0, v232, s[12:13]
	v_cmp_gt_f32_e64 s[12:13], v210, v38
	v_addc_co_u32_e64 v232, s[18:19], 0, v232, s[14:15]
	v_cmp_gt_f32_e64 s[14:15], v211, v38
	v_addc_co_u32_e64 v232, s[18:19], 0, v232, s[16:17]
	v_cmp_gt_f32_e64 s[16:17], v212, v38
	v_addc_co_u32_e64 v232, s[18:19], 0, v232, s[12:13]
	v_cmp_gt_f32_e64 s[12:13], v213, v38
	v_addc_co_u32_e64 v232, s[18:19], 0, v232, s[14:15]
	v_cmp_gt_f32_e64 s[14:15], v214, v38
	v_addc_co_u32_e64 v232, s[18:19], 0, v232, s[16:17]
	v_cmp_gt_f32_e64 s[16:17], v215, v38
	v_addc_co_u32_e64 v232, s[18:19], 0, v232, s[12:13]
	v_cmp_gt_f32_e64 s[12:13], v216, v38
	v_addc_co_u32_e64 v232, s[18:19], 0, v232, s[14:15]
	v_cmp_gt_f32_e64 s[14:15], v217, v38
	v_addc_co_u32_e64 v232, s[18:19], 0, v232, s[16:17]
	v_cmp_gt_f32_e64 s[16:17], v218, v38
	v_addc_co_u32_e64 v232, s[18:19], 0, v232, s[12:13]
	v_cmp_gt_f32_e64 s[12:13], v219, v38
	v_addc_co_u32_e64 v232, s[18:19], 0, v232, s[14:15]
	v_cmp_gt_f32_e64 s[14:15], v220, v38
	v_addc_co_u32_e64 v232, s[18:19], 0, v232, s[16:17]
	v_cmp_gt_f32_e64 s[16:17], v221, v38
	v_addc_co_u32_e64 v232, s[18:19], 0, v232, s[12:13]
	v_cmp_gt_f32_e64 s[12:13], v222, v38
	v_addc_co_u32_e64 v232, s[18:19], 0, v232, s[14:15]
	v_cmp_gt_f32_e64 s[14:15], v223, v38
	v_addc_co_u32_e64 v232, s[18:19], 0, v232, s[16:17]
	v_cmp_gt_f32_e64 s[16:17], v224, v38
	v_addc_co_u32_e64 v232, s[18:19], 0, v232, s[12:13]
	v_cmp_gt_f32_e64 s[12:13], v225, v38
	v_addc_co_u32_e64 v232, s[18:19], 0, v232, s[14:15]
	v_cmp_gt_f32_e64 s[14:15], v226, v38
	v_addc_co_u32_e64 v232, s[18:19], 0, v232, s[16:17]
	v_cmp_gt_f32_e64 s[16:17], v227, v38
	v_addc_co_u32_e64 v232, s[18:19], 0, v232, s[12:13]
	v_cmp_gt_f32_e64 s[12:13], v228, v38
	v_addc_co_u32_e64 v232, s[18:19], 0, v232, s[14:15]
	v_cmp_gt_f32_e64 s[14:15], v229, v38
	v_addc_co_u32_e64 v232, s[18:19], 0, v232, s[16:17]
	s_nop 1
	v_addc_co_u32_e64 v232, s[18:19], 0, v232, s[12:13]
	v_addc_co_u32_e64 v232, s[18:19], 0, v232, s[14:15]
	v_cmp_gt_u32_e64 s[12:13], 8, v232
	v_cmp_ge_i32_e64 s[14:15], s54, v240
	v_lshlrev_b32_e64 v240, v240, 1
	s_and_b64 s[12:13], s[12:13], s[14:15]
	s_nop 1
	v_cndmask_b32_e64 v240, 0, v240, s[12:13]
.Lrk_sk_l2:
	s_cmp_gt_i32 s54, 11
	s_cbranch_scc1 .Lrk_do_l3
	v_mov_b32_e32 v241, 0
	s_branch .Lrk_sk_l3
; #define LAS __attribute__((address_space(3)))
; DI void attn_phase(const Params& p, const int layer, const int wid_s) {
;     ...
;       for (int i = 0; i < 8; ++i) {
;         const f32x4 r4 = *(const LAS f32x4*)(impb + 4 * i);
;         const float rv[4] = {r4[0], r4[1], r4[2], r4[3]};
; #pragma unroll
;         for (int nt = 0; nt < 8; ++nt) {
;           const float a = impv[nt]; const int ja = nt * 4 + fql;
; #pragma unroll
;           for (int c = 0; c < 4; ++c) cnt[nt] += (int)(rv[c] > a) | ((int)(rv[c] == a) & (int)((4 * i + c) < ja));
;         }
;       }
;       mk = 0;
; #pragma unroll
;       for (int nt = 0; nt < 8; ++nt) { const int ja = nt * 4 + fql; if (cnt[nt] < 8 && ja <= cur) mk |= 1u << ja; }
.Lrk_do_l3:
	v_cmp_ge_f32_e64 s[12:13], v198, v37
	v_cmp_ge_f32_e64 s[14:15], v199, v37
	v_cmp_ge_f32_e64 s[16:17], v200, v37
	v_addc_co_u32_e64 v233, s[18:19], 0, v233, s[12:13]
	v_cmp_ge_f32_e64 s[12:13], v201, v37
	v_addc_co_u32_e64 v233, s[18:19], 0, v233, s[14:15]
	v_cmp_ge_f32_e64 s[14:15], v202, v37
	v_addc_co_u32_e64 v233, s[18:19], 0, v233, s[16:17]
	v_cmp_ge_f32_e64 s[16:17], v203, v37
	v_addc_co_u32_e64 v233, s[18:19], 0, v233, s[12:13]
	v_cmp_ge_f32_e64 s[12:13], v204, v37
	v_addc_co_u32_e64 v233, s[18:19], 0, v233, s[14:15]
	v_cmp_ge_f32_e64 s[14:15], v205, v37
	v_addc_co_u32_e64 v233, s[18:19], 0, v233, s[16:17]
	v_cmp_ge_f32_e64 s[16:17], v206, v37
	v_addc_co_u32_e64 v233, s[18:19], 0, v233, s[12:13]
	v_cmp_ge_f32_e64 s[12:13], v207, v37
	v_addc_co_u32_e64 v233, s[18:19], 0, v233, s[14:15]
	v_cmp_ge_f32_e64 s[14:15], v208, v37
	v_addc_co_u32_e64 v233, s[18:19], 0, v233, s[16:17]
	v_cmp_ge_f32_e64 s[16:17], v209, v37
	v_addc_co_u32_e64 v233, s[18:19], 0, v233, s[12:13]
	v_cmp_gt_f32_e64 s[12:13], v210, v37
	v_cmp_ge_f32_e64 s[20:21], v210, v37
	s_and_b64 s[20:21], s[20:21], s[6:7]
	s_or_b64 s[12:13], s[12:13], s[20:21]
	v_addc_co_u32_e64 v233, s[18:19], 0, v233, s[14:15]
	v_cmp_gt_f32_e64 s[14:15], v211, v37
	v_cmp_ge_f32_e64 s[20:21], v211, v37
	s_and_b64 s[20:21], s[20:21], s[8:9]
	s_or_b64 s[14:15], s[14:15], s[20:21]
	v_addc_co_u32_e64 v233, s[18:19], 0, v233, s[16:17]
	v_cmp_gt_f32_e64 s[16:17], v212, v37
	v_cmp_ge_f32_e64 s[20:21], v212, v37
	s_and_b64 s[20:21], s[20:21], s[10:11]
	s_or_b64 s[16:17], s[16:17], s[20:21]
	v_addc_co_u32_e64 v233, s[18:19], 0, v233, s[12:13]
	v_cmp_gt_f32_e64 s[12:13], v213, v37
	v_addc_co_u32_e64 v233, s[18:19], 0, v233, s[14:15]
	v_cmp_gt_f32_e64 s[14:15], v214, v37
	v_addc_co_u32_e64 v233, s[18:19], 0, v233, s[16:17]
	v_cmp_gt_f32_e64 s[16:17], v215, v37
	v_addc_co_u32_e64 v233, s[18:19], 0, v233, s[12:13]
	v_cmp_gt_f32_e64 s[12:13], v216, v37
	v_addc_co_u32_e64 v233, s[18:19], 0, v233, s[14:15]
	v_cmp_gt_f32_e64 s[14:15], v217, v37
	v_addc_co_u32_e64 v233, s[18:19], 0, v233, s[16:17]
	v_cmp_gt_f32_e64 s[16:17], v218, v37
	v_addc_co_u32_e64 v233, s[18:19], 0, v233, s[12:13]
	v_cmp_gt_f32_e64 s[12:13], v219, v37
	v_addc_co_u32_e64 v233, s[18:19], 0, v233, s[14:15]
	v_cmp_gt_f32_e64 s[14:15], v220, v37
	v_addc_co_u32_e64 v233, s[18:19], 0, v233, s[16:17]
	v_cmp_gt_f32_e64 s[16:17], v221, v37
	v_addc_co_u32_e64 v233, s[18:19], 0, v233, s[12:13]
	v_cmp_gt_f32_e64 s[12:13], v222, v37
	v_addc_co_u32_e64 v233, s[18:19], 0, v233, s[14:15]
	v_cmp_gt_f32_e64 s[14:15], v223, v37
	v_addc_co_u32_e64 v233, s[18:19], 0, v233, s[16:17]
	v_cmp_gt_f32_e64 s[16:17], v224, v37
	v_addc_co_u32_e64 v233, s[18:19], 0, v233, s[12:13]
	v_cmp_gt_f32_e64 s[12:13], v225, v37
	v_addc_co_u32_e64 v233, s[18:19], 0, v233, s[14:15]
	v_cmp_gt_f32_e64 s[14:15], v226, v37
	v_addc_co_u32_e64 v233, s[18:19], 0, v233, s[16:17]
	v_cmp_gt_f32_e64 s[16:17], v227, v37
	v_addc_co_u32_e64 v233, s[18:19], 0, v233, s[12:13]
	v_cmp_gt_f32_e64 s[12:13], v228, v37
	v_addc_co_u32_e64 v233, s[18:19], 0, v233, s[14:15]
	v_cmp_gt_f32_e64 s[14:15], v229, v37
	v_addc_co_u32_e64 v233, s[18:19], 0, v233, s[16:17]
	s_nop 1
	v_addc_co_u32_e64 v233, s[18:19], 0, v233, s[12:13]
	v_addc_co_u32_e64 v233, s[18:19], 0, v233, s[14:15]
	v_cmp_gt_u32_e64 s[16:17], 8, v233
	v_cmp_ge_i32_e64 s[20:21], s54, v241
	v_lshlrev_b32_e64 v241, v241, 1
	s_and_b64 s[16:17], s[16:17], s[20:21]
	s_nop 1
	v_cndmask_b32_e64 v241, 0, v241, s[16:17]
.Lrk_sk_l3:
	v_or_b32_e32 v0, v238, v239
	v_or3_b32 v0, v0, v240, v241
